# o5 with lgkmcnt(15) waits tightened to lgkmcnt(14) in the scan loop (robust to a saturating counter); otherwise identical
# speedup vs baseline: 1.0092x; 1.0092x over previous
.LBB0_1544:
	s_bitcmp1_b32 s5, 0
	s_cselect_b32 s25, 0x13000, 0
	s_add_i32 s25, s25, 0
	v_add_u32_e32 v130, s25, v146
	v_add_u32_e32 v131, v130, v126
	v_add3_u32 v110, s25, v125, v124
	v_add_u32_e32 v144, 0x1000, v131
	v_add_u32_e32 v145, 0x2000, v131
	v_add_u32_e32 v180, 0x3000, v131
	ds_read_b64 v[98:99], v110 offset:61440
	ds_read_b64 v[100:101], v110 offset:61952
	ds_read_b64 v[102:103], v110 offset:62464
	ds_read_b64 v[104:105], v110 offset:62976
	ds_read_b64 v[106:107], v110 offset:63488
	ds_read_b64 v[108:109], v110 offset:64000
	ds_read_b64 v[112:113], v110 offset:65024
	ds_read_b64 v[110:111], v110 offset:64512
	ds_read_b64 v[114:115], v131
	ds_read_b64 v[116:117], v131 offset:32
	ds_read_b64 v[132:133], v131 offset:64
	ds_read_b64 v[134:135], v131 offset:96
	ds_read_b64 v[136:137], v144 offset:256
	ds_read_b64 v[138:139], v144 offset:288
	ds_read_b64 v[140:141], v144 offset:320
	ds_read_b64 v[142:143], v144 offset:352
	ds_read_b64 v[148:149], v145 offset:512
	ds_read_b64 v[150:151], v145 offset:544
	ds_read_b64 v[152:153], v145 offset:576
	ds_read_b64 v[154:155], v145 offset:608
	ds_read_b64 v[156:157], v180 offset:768
	ds_read_b64 v[158:159], v180 offset:800
	ds_read_b64 v[160:161], v180 offset:832
	ds_read_b64 v[162:163], v180 offset:864
	v_readlane_b32 s4, v123, s5
	v_cvt_pk_bf16_f32 v78, v62, v63
	v_cvt_pk_bf16_f32 v79, v64, v65
	v_cvt_pk_bf16_f32 v80, v54, v55
	v_cvt_pk_bf16_f32 v81, v56, v57
	v_cvt_pk_bf16_f32 v86, v58, v59
	v_cvt_pk_bf16_f32 v87, v60, v61
	v_cvt_pk_bf16_f32 v88, v46, v47
	v_cvt_pk_bf16_f32 v89, v48, v49
	v_cvt_pk_bf16_f32 v90, v50, v51
	v_cvt_pk_bf16_f32 v91, v52, v53
	v_cvt_pk_bf16_f32 v92, v42, v43
	v_cvt_pk_bf16_f32 v93, v44, v45
	v_cvt_pk_bf16_f32 v94, v38, v39
	v_cvt_pk_bf16_f32 v95, v40, v41
	v_cvt_pk_bf16_f32 v96, v34, v35
	v_cvt_pk_bf16_f32 v97, v36, v37
	v_cvt_pk_bf16_f32 v66, v30, v31
	v_cvt_pk_bf16_f32 v67, v32, v33
	v_cvt_pk_bf16_f32 v68, v26, v27
	v_cvt_pk_bf16_f32 v69, v28, v29
	v_cvt_pk_bf16_f32 v74, v22, v23
	v_cvt_pk_bf16_f32 v75, v24, v25
	v_cvt_pk_bf16_f32 v76, v14, v15
	v_cvt_pk_bf16_f32 v77, v16, v17
	v_cvt_pk_bf16_f32 v70, v18, v19
	v_cvt_pk_bf16_f32 v71, v20, v21
	v_cvt_pk_bf16_f32 v72, v10, v11
	v_cvt_pk_bf16_f32 v73, v12, v13
	v_cvt_pk_bf16_f32 v82, v6, v7
	v_cvt_pk_bf16_f32 v83, v8, v9
	v_cvt_pk_bf16_f32 v84, v2, v3
	v_cvt_pk_bf16_f32 v85, v4, v5
	s_waitcnt lgkmcnt(14)
	v_lshlrev_b32_e32 v164, 16, v98
	v_and_b32_e32 v165, 0xffff0000, v98
	v_lshlrev_b32_e32 v166, 16, v99
	v_and_b32_e32 v167, 0xffff0000, v99
	s_waitcnt lgkmcnt(14)
	v_lshlrev_b32_e32 v168, 16, v106
	v_and_b32_e32 v169, 0xffff0000, v106
	v_lshlrev_b32_e32 v170, 16, v107
	v_and_b32_e32 v171, 0xffff0000, v107
	v_lshlrev_b32_e32 v98, 16, v100
	v_and_b32_e32 v99, 0xffff0000, v100
	v_lshlrev_b32_e32 v100, 16, v101
	v_and_b32_e32 v101, 0xffff0000, v101
	v_lshlrev_b32_e32 v106, 16, v108
	v_and_b32_e32 v107, 0xffff0000, v108
	v_lshlrev_b32_e32 v108, 16, v109
	v_and_b32_e32 v109, 0xffff0000, v109
	v_lshlrev_b32_e32 v172, 16, v102
	v_and_b32_e32 v173, 0xffff0000, v102
	v_lshlrev_b32_e32 v174, 16, v103
	v_and_b32_e32 v175, 0xffff0000, v103
	s_waitcnt lgkmcnt(14)
	v_lshlrev_b32_e32 v176, 16, v110
	v_and_b32_e32 v177, 0xffff0000, v110
	v_lshlrev_b32_e32 v178, 16, v111
	v_and_b32_e32 v179, 0xffff0000, v111
	v_lshlrev_b32_e32 v102, 16, v104
	v_and_b32_e32 v103, 0xffff0000, v104
	v_lshlrev_b32_e32 v104, 16, v105
	v_and_b32_e32 v105, 0xffff0000, v105
	v_lshlrev_b32_e32 v110, 16, v112
	v_and_b32_e32 v111, 0xffff0000, v112
	v_lshlrev_b32_e32 v112, 16, v113
	v_and_b32_e32 v113, 0xffff0000, v113
	s_waitcnt lgkmcnt(14)
	v_mfma_f32_16x16x32_bf16 v[164:167], v[114:117], v[78:81], v[164:167]
	v_mfma_f32_16x16x32_bf16 v[114:117], v[114:117], v[86:89], v[168:171]
	s_waitcnt lgkmcnt(10)
	v_mfma_f32_16x16x32_bf16 v[98:101], v[136:139], v[78:81], v[98:101]
	v_mfma_f32_16x16x32_bf16 v[106:109], v[136:139], v[86:89], v[106:109]
	s_waitcnt lgkmcnt(6)
	v_mfma_f32_16x16x32_bf16 v[136:139], v[148:151], v[78:81], v[172:175]
	v_mfma_f32_16x16x32_bf16 v[148:151], v[148:151], v[86:89], v[176:179]
	s_waitcnt lgkmcnt(2)
	v_mfma_f32_16x16x32_bf16 v[102:105], v[156:159], v[78:81], v[102:105]
	v_mfma_f32_16x16x32_bf16 v[110:113], v[156:159], v[86:89], v[110:113]
	v_mfma_f32_16x16x32_bf16 v[156:159], v[132:135], v[90:93], v[164:167]
	v_mfma_f32_16x16x32_bf16 v[114:117], v[132:135], v[94:97], v[114:117]
	v_mfma_f32_16x16x32_bf16 v[98:101], v[140:143], v[90:93], v[98:101]
	v_mfma_f32_16x16x32_bf16 v[106:109], v[140:143], v[94:97], v[106:109]
	v_mfma_f32_16x16x32_bf16 v[132:135], v[152:155], v[90:93], v[136:139]
	s_nop 2
	ds_read_b64 v[136:137], v131 offset:128
	ds_read_b64 v[138:139], v131 offset:160
	ds_read_b64 v[140:141], v131 offset:192
	ds_read_b64 v[142:143], v131 offset:224
	v_mfma_f32_16x16x32_bf16 v[148:151], v[152:155], v[94:97], v[148:151]
	ds_read_b64 v[152:153], v144 offset:384
	ds_read_b64 v[154:155], v144 offset:416
	ds_read_b64 v[164:165], v144 offset:448
	ds_read_b64 v[166:167], v144 offset:480
	ds_read_b64 v[168:169], v145 offset:640
	ds_read_b64 v[170:171], v145 offset:672
	ds_read_b64 v[172:173], v145 offset:704
	ds_read_b64 v[174:175], v145 offset:736
	ds_read_b64 v[176:177], v180 offset:896
	ds_read_b64 v[178:179], v180 offset:928
	ds_read_b64 v[182:183], v180 offset:992
	ds_read_b64 v[180:181], v180 offset:960
	s_waitcnt lgkmcnt(14)
	v_mfma_f32_16x16x32_bf16 v[102:105], v[160:163], v[90:93], v[102:105]
	v_mfma_f32_16x16x32_bf16 v[110:113], v[160:163], v[94:97], v[110:113]
	s_add_i32 s25, s25, 0x8800
	s_waitcnt lgkmcnt(14)
	v_mfma_f32_16x16x32_bf16 v[156:159], v[136:139], v[66:69], v[156:159]
	v_add_u32_e32 v144, s25, v129
	v_mfma_f32_16x16x32_bf16 v[114:117], v[136:139], v[74:77], v[114:117]
	ds_read_b64_tr_b16 v[136:137], v144
	ds_read_b64_tr_b16 v[138:139], v144 offset:4352
	s_waitcnt lgkmcnt(8)
	v_mfma_f32_16x16x32_bf16 v[98:101], v[152:155], v[66:69], v[98:101]
	v_mfma_f32_16x16x32_bf16 v[106:109], v[152:155], v[74:77], v[106:109]
	ds_read_b64_tr_b16 v[152:153], v144 offset:8704
	ds_read_b64_tr_b16 v[154:155], v144 offset:13056
	ds_read_b64_tr_b16 v[160:161], v144 offset:32
	s_waitcnt lgkmcnt(3)
	v_mfma_f32_16x16x32_bf16 v[132:135], v[168:171], v[66:69], v[132:135]
	v_mfma_f32_16x16x32_bf16 v[148:151], v[168:171], v[74:77], v[148:151]
	ds_read_b64_tr_b16 v[162:163], v144 offset:4384
	ds_read_b64_tr_b16 v[168:169], v144 offset:8736
	ds_read_b64_tr_b16 v[170:171], v144 offset:13088
	v_mfma_f32_16x16x32_bf16 v[156:159], v[140:143], v[70:73], v[156:159]
	v_mfma_f32_16x16x32_bf16 v[114:117], v[140:143], v[82:85], v[114:117]
	ds_read_b64_tr_b16 v[140:141], v144 offset:64
	ds_read_b64_tr_b16 v[142:143], v144 offset:4416
	s_waitcnt lgkmcnt(1)
	v_mfma_f32_16x16x32_bf16 v[102:105], v[176:179], v[66:69], v[102:105]
	v_mfma_f32_16x16x32_bf16 v[110:113], v[176:179], v[74:77], v[110:113]
	v_mfma_f32_16x16x32_bf16 v[176:179], v[164:167], v[70:73], v[98:101]
	s_nop 2
	ds_read_b64_tr_b16 v[184:185], v144 offset:8768
	ds_read_b64_tr_b16 v[186:187], v144 offset:13120
	v_mfma_f32_16x16x32_bf16 v[106:109], v[164:167], v[82:85], v[106:109]
	ds_read_b64_tr_b16 v[164:165], v144 offset:96
	ds_read_b64_tr_b16 v[166:167], v144 offset:4448
	v_mfma_f32_16x16x32_bf16 v[132:135], v[172:175], v[70:73], v[132:135]
	v_mfma_f32_16x16x32_bf16 v[148:151], v[172:175], v[82:85], v[148:151]
	ds_read_b64_tr_b16 v[172:173], v144 offset:8800
	ds_read_b64_tr_b16 v[174:175], v144 offset:13152
	s_waitcnt lgkmcnt(0)
	v_mfma_f32_16x16x32_bf16 v[188:191], v[180:183], v[70:73], v[102:105]
	s_waitcnt lgkmcnt(0)
	v_mfma_f32_16x16x32_bf16 v[180:183], v[180:183], v[82:85], v[110:113]
	v_cvt_pk_bf16_f32 v98, v156, v157
	v_cvt_pk_bf16_f32 v99, v158, v159
	v_cvt_pk_bf16_f32 v100, v176, v177
	v_cvt_pk_bf16_f32 v101, v178, v179
	v_cvt_pk_bf16_f32 v102, v114, v115
	v_cvt_pk_bf16_f32 v103, v116, v117
	v_cvt_pk_bf16_f32 v104, v106, v107
	v_cvt_pk_bf16_f32 v105, v108, v109
	v_pk_mul_f32 v[64:65], v[64:65], s[4:5] op_sel_hi:[1,0]
	v_pk_mul_f32 v[62:63], v[62:63], s[4:5] op_sel_hi:[1,0]
	v_pk_mul_f32 v[60:61], v[60:61], s[4:5] op_sel_hi:[1,0]
	v_pk_mul_f32 v[58:59], v[58:59], s[4:5] op_sel_hi:[1,0]
	v_mfma_f32_16x16x32_bf16 v[62:65], v[136:139], v[98:101], v[62:65]
	v_mul_f32_e64 v56, v56, s4
	v_mul_f32_e64 v57, v57, s4
	v_pk_mul_f32 v[54:55], v[54:55], s[4:5] op_sel_hi:[1,0]
	v_pk_mul_f32 v[48:49], v[48:49], s[4:5] op_sel_hi:[1,0]
	v_mfma_f32_16x16x32_bf16 v[58:61], v[136:139], v[102:105], v[58:61]
	v_mul_f32_e64 v46, v46, s4
	v_mul_f32_e64 v47, v47, s4
	v_pk_mul_f32 v[52:53], v[52:53], s[4:5] op_sel_hi:[1,0]
	v_pk_mul_f32 v[50:51], v[50:51], s[4:5] op_sel_hi:[1,0]
	v_pk_mul_f32 v[40:41], v[40:41], s[4:5] op_sel_hi:[1,0]
	v_pk_mul_f32 v[38:39], v[38:39], s[4:5] op_sel_hi:[1,0]
	v_pk_mul_f32 v[44:45], v[44:45], s[4:5] op_sel_hi:[1,0]
	v_pk_mul_f32 v[42:43], v[42:43], s[4:5] op_sel_hi:[1,0]
	v_pk_mul_f32 v[36:37], v[36:37], s[4:5] op_sel_hi:[1,0]
	v_pk_mul_f32 v[34:35], v[34:35], s[4:5] op_sel_hi:[1,0]
	v_mfma_f32_16x16x32_bf16 v[54:57], v[160:163], v[98:101], v[54:57]
	v_cvt_pk_bf16_f32 v106, v132, v133
	v_cvt_pk_bf16_f32 v107, v134, v135
	v_cvt_pk_bf16_f32 v108, v188, v189
	v_mfma_f32_16x16x32_bf16 v[46:49], v[160:163], v[102:105], v[46:49]
	v_cvt_pk_bf16_f32 v109, v190, v191
	v_cvt_pk_bf16_f32 v110, v148, v149
	v_cvt_pk_bf16_f32 v111, v150, v151
	v_mfma_f32_16x16x32_bf16 v[50:53], v[140:143], v[98:101], v[50:53]
	v_cvt_pk_bf16_f32 v112, v180, v181
	v_cvt_pk_bf16_f32 v113, v182, v183
	v_add_u32_e32 v145, 0x4000, v131
	v_mfma_f32_16x16x32_bf16 v[38:41], v[140:143], v[102:105], v[38:41]
	v_add_u32_e32 v196, 0x5000, v131
	v_add_u32_e32 v197, 0x6000, v131
	v_add_u32_e32 v131, 0x7000, v131
	v_mfma_f32_16x16x32_bf16 v[42:45], v[164:167], v[98:101], v[42:45]
	ds_read_b64 v[132:133], v145 offset:1024
	ds_read_b64 v[134:135], v145 offset:1056
	ds_read_b64 v[114:115], v145 offset:1088
	ds_read_b64 v[116:117], v145 offset:1120
	ds_read_b64 v[136:137], v196 offset:1280
	ds_read_b64 v[138:139], v196 offset:1312
	ds_read_b64 v[140:141], v196 offset:1344
	ds_read_b64 v[142:143], v196 offset:1376
	v_mfma_f32_16x16x32_bf16 v[34:37], v[164:167], v[102:105], v[34:37]
	v_mfma_f32_16x16x32_bf16 v[62:65], v[152:155], v[106:109], v[62:65]
	v_mfma_f32_16x16x32_bf16 v[58:61], v[152:155], v[110:113], v[58:61]
	ds_read_b64 v[148:149], v197 offset:1536
	ds_read_b64 v[150:151], v197 offset:1568
	ds_read_b64 v[152:153], v197 offset:1600
	ds_read_b64 v[154:155], v197 offset:1632
	ds_read_b64 v[156:157], v131 offset:1792
	ds_read_b64 v[158:159], v131 offset:1824
	ds_read_b64 v[160:161], v131 offset:1856
	ds_read_b64 v[162:163], v131 offset:1888
	v_mfma_f32_16x16x32_bf16 v[54:57], v[168:171], v[106:109], v[54:57]
	v_mfma_f32_16x16x32_bf16 v[46:49], v[168:171], v[110:113], v[46:49]
	v_mfma_f32_16x16x32_bf16 v[50:53], v[184:187], v[106:109], v[50:53]
	v_mfma_f32_16x16x32_bf16 v[38:41], v[184:187], v[110:113], v[38:41]
	v_mfma_f32_16x16x32_bf16 v[42:45], v[172:175], v[106:109], v[42:45]
	v_mfma_f32_16x16x32_bf16 v[34:37], v[172:175], v[110:113], v[34:37]
	ds_read_b64_tr_b16 v[164:165], v144 offset:128
	ds_read_b64_tr_b16 v[166:167], v144 offset:4480
	ds_read_b64_tr_b16 v[168:169], v144 offset:8832
	ds_read_b64_tr_b16 v[170:171], v144 offset:13184
	ds_read_b64_tr_b16 v[172:173], v144 offset:160
	ds_read_b64_tr_b16 v[174:175], v144 offset:4512
	ds_read_b64_tr_b16 v[176:177], v144 offset:8864
	ds_read_b64_tr_b16 v[178:179], v144 offset:13216
	ds_read_b64_tr_b16 v[180:181], v144 offset:192
	ds_read_b64_tr_b16 v[182:183], v144 offset:4544
	ds_read_b64_tr_b16 v[184:185], v144 offset:8896
	ds_read_b64_tr_b16 v[186:187], v144 offset:13248
	ds_read_b64_tr_b16 v[188:189], v144 offset:224
	ds_read_b64_tr_b16 v[190:191], v144 offset:4576
	ds_read_b64_tr_b16 v[192:193], v144 offset:8928
	ds_read_b64_tr_b16 v[194:195], v144 offset:13280
	s_nop 0
	s_waitcnt lgkmcnt(0)
	v_pk_mul_f32 v[32:33], v[32:33], s[4:5] op_sel_hi:[1,0]
	v_pk_mul_f32 v[30:31], v[30:31], s[4:5] op_sel_hi:[1,0]
	v_pk_mul_f32 v[24:25], v[24:25], s[4:5] op_sel_hi:[1,0]
	v_pk_mul_f32 v[22:23], v[22:23], s[4:5] op_sel_hi:[1,0]
	v_mfma_f32_16x16x32_bf16 v[30:33], v[164:167], v[98:101], v[30:33]
	v_mul_f32_e64 v28, v28, s4
	v_mul_f32_e64 v29, v29, s4
	v_pk_mul_f32 v[26:27], v[26:27], s[4:5] op_sel_hi:[1,0]
	v_pk_mul_f32 v[16:17], v[16:17], s[4:5] op_sel_hi:[1,0]
	v_mfma_f32_16x16x32_bf16 v[22:25], v[164:167], v[102:105], v[22:25]
	v_mul_f32_e64 v14, v14, s4
	v_mul_f32_e64 v15, v15, s4
	v_pk_mul_f32 v[20:21], v[20:21], s[4:5] op_sel_hi:[1,0]
	v_pk_mul_f32 v[18:19], v[18:19], s[4:5] op_sel_hi:[1,0]
	v_pk_mul_f32 v[8:9], v[8:9], s[4:5] op_sel_hi:[1,0]
	v_pk_mul_f32 v[6:7], v[6:7], s[4:5] op_sel_hi:[1,0]
	v_mfma_f32_16x16x32_bf16 v[30:33], v[168:171], v[106:109], v[30:33]
	v_mul_f32_e64 v12, v12, s4
	v_mul_f32_e64 v13, v13, s4
	v_pk_mul_f32 v[10:11], v[10:11], s[4:5] op_sel_hi:[1,0]
	v_pk_mul_f32 v[4:5], v[4:5], s[4:5] op_sel_hi:[1,0]
	v_mfma_f32_16x16x32_bf16 v[22:25], v[168:171], v[110:113], v[22:25]
	v_mul_f32_e64 v2, v2, s4
	v_mul_f32_e64 v3, v3, s4
	v_mfma_f32_16x16x32_bf16 v[26:29], v[172:175], v[98:101], v[26:29]
	v_mfma_f32_16x16x32_bf16 v[14:17], v[172:175], v[102:105], v[14:17]
	v_mfma_f32_16x16x32_bf16 v[18:21], v[180:183], v[98:101], v[18:21]
	v_mfma_f32_16x16x32_bf16 v[6:9], v[180:183], v[102:105], v[6:9]
	s_waitcnt lgkmcnt(7)
	v_mfma_f32_16x16x32_bf16 v[164:167], v[78:81], v[132:135], 0
	v_mfma_f32_16x16x32_bf16 v[132:135], v[86:89], v[132:135], 0
	s_waitcnt lgkmcnt(5)
	v_mfma_f32_16x16x32_bf16 v[168:171], v[78:81], v[136:139], 0
	v_mfma_f32_16x16x32_bf16 v[136:139], v[86:89], v[136:139], 0
	s_waitcnt lgkmcnt(3)
	v_mfma_f32_16x16x32_bf16 v[172:175], v[78:81], v[148:151], 0
	v_mfma_f32_16x16x32_bf16 v[148:151], v[86:89], v[148:151], 0
	s_waitcnt lgkmcnt(1)
	v_mfma_f32_16x16x32_bf16 v[78:81], v[78:81], v[156:159], 0
	v_mfma_f32_16x16x32_bf16 v[10:13], v[188:191], v[98:101], v[10:13]
	v_mfma_f32_16x16x32_bf16 v[2:5], v[188:191], v[102:105], v[2:5]
	v_mfma_f32_16x16x32_bf16 v[26:29], v[176:179], v[106:109], v[26:29]
	v_mfma_f32_16x16x32_bf16 v[14:17], v[176:179], v[110:113], v[14:17]
	v_mfma_f32_16x16x32_bf16 v[18:21], v[184:187], v[106:109], v[18:21]
	v_mfma_f32_16x16x32_bf16 v[6:9], v[184:187], v[110:113], v[6:9]
	v_mfma_f32_16x16x32_bf16 v[86:89], v[86:89], v[156:159], 0
	v_mfma_f32_16x16x32_bf16 v[156:159], v[90:93], v[114:117], v[164:167]
	v_mfma_f32_16x16x32_bf16 v[114:117], v[94:97], v[114:117], v[132:135]
	v_mfma_f32_16x16x32_bf16 v[132:135], v[90:93], v[140:143], v[168:171]
	s_nop 0
	ds_read_b64 v[164:165], v145 offset:1152
	ds_read_b64 v[166:167], v145 offset:1184
	s_nop 0
	ds_read_b64 v[168:169], v145 offset:1216
	ds_read_b64 v[170:171], v145 offset:1248
	v_mfma_f32_16x16x32_bf16 v[136:139], v[94:97], v[140:143], v[136:139]
	v_mfma_f32_16x16x32_bf16 v[140:143], v[90:93], v[152:155], v[172:175]
	v_mfma_f32_16x16x32_bf16 v[148:151], v[94:97], v[152:155], v[148:151]
	ds_read_b64 v[152:153], v196 offset:1408
	ds_read_b64 v[154:155], v196 offset:1440
	s_nop 0
	ds_read_b64 v[172:173], v196 offset:1472
	ds_read_b64 v[174:175], v196 offset:1504
	ds_read_b64 v[176:177], v197 offset:1664
	ds_read_b64 v[178:179], v197 offset:1696
	s_waitcnt lgkmcnt(10)
	v_mfma_f32_16x16x32_bf16 v[78:81], v[90:93], v[160:163], v[78:81]
	ds_read_b64 v[90:91], v197 offset:1728
	ds_read_b64 v[92:93], v197 offset:1760
	ds_read_b64 v[180:181], v131 offset:1920
	ds_read_b64 v[182:183], v131 offset:1952
	ds_read_b64 v[184:185], v131 offset:1984
	ds_read_b64 v[186:187], v131 offset:2016
	v_mfma_f32_16x16x32_bf16 v[10:13], v[192:195], v[106:109], v[10:13]
	v_mfma_f32_16x16x32_bf16 v[2:5], v[192:195], v[110:113], v[2:5]
	v_mfma_f32_16x16x32_bf16 v[86:89], v[94:97], v[160:163], v[86:89]
	s_waitcnt lgkmcnt(14)
	v_mfma_f32_16x16x32_bf16 v[94:97], v[66:69], v[164:167], v[156:159]
	v_add_u32_e32 v160, v130, v127
	s_waitcnt lgkmcnt(10)
	v_mfma_f32_16x16x32_bf16 v[132:135], v[66:69], v[152:155], v[132:135]
	v_add_u32_e32 v156, 0xd800, v160
	v_mfma_f32_16x16x32_bf16 v[114:117], v[74:77], v[164:167], v[114:117]
	v_mfma_f32_16x16x32_bf16 v[136:139], v[74:77], v[152:155], v[136:139]
	v_add_u32_e32 v152, 0xd000, v160
	s_waitcnt lgkmcnt(6)
	v_mfma_f32_16x16x32_bf16 v[140:143], v[66:69], v[176:179], v[140:143]
	v_mfma_f32_16x16x32_bf16 v[148:151], v[74:77], v[176:179], v[148:151]
	s_waitcnt lgkmcnt(2)
	v_mfma_f32_16x16x32_bf16 v[66:69], v[66:69], v[180:183], v[78:81]
	v_mfma_f32_16x16x32_bf16 v[78:81], v[70:73], v[168:171], v[94:97]
	v_mfma_f32_16x16x32_bf16 v[94:97], v[70:73], v[172:175], v[132:135]
	s_nop 2
	v_add_u32_e32 v134, 0xc800, v160
	v_add_u32_e32 v160, 0xe000, v160
	v_mfma_f32_16x16x32_bf16 v[74:77], v[74:77], v[180:183], v[86:89]
	v_mfma_f32_16x16x32_bf16 v[86:89], v[82:85], v[168:171], v[114:117]
	v_mfma_f32_16x16x32_bf16 v[114:117], v[82:85], v[172:175], v[136:139]
	ds_read_b64 v[130:131], v134 offset:1024
	ds_read_b64 v[132:133], v134 offset:1056
	s_nop 1
	ds_read_b64 v[136:137], v134 offset:1120
	ds_read_b64 v[134:135], v134 offset:1088
	v_mfma_f32_16x16x32_bf16 v[138:141], v[70:73], v[90:93], v[140:143]
	s_nop 2
	ds_read_b64 v[142:143], v152 offset:1280
	ds_read_b64 v[144:145], v152 offset:1312
	ds_read_b64 v[154:155], v152 offset:1376
	ds_read_b64 v[152:153], v152 offset:1344
	v_mfma_f32_16x16x32_bf16 v[90:93], v[82:85], v[90:93], v[148:151]
	s_nop 2
	ds_read_b64 v[148:149], v156 offset:1536
	ds_read_b64 v[150:151], v156 offset:1568
	ds_read_b64 v[158:159], v156 offset:1632
	ds_read_b64 v[156:157], v156 offset:1600
	s_waitcnt lgkmcnt(12)
	v_mfma_f32_16x16x32_bf16 v[66:69], v[70:73], v[184:187], v[66:69]
	ds_read_b64 v[70:71], v160 offset:1792
	ds_read_b64 v[72:73], v160 offset:1824
	ds_read_b64 v[162:163], v160 offset:1888
	ds_read_b64 v[160:161], v160 offset:1856
	v_mfma_f32_16x16x32_bf16 v[74:77], v[82:85], v[184:187], v[74:77]
	s_waitcnt lgkmcnt(14)
	v_mfma_f32_16x16x32_bf16 v[78:81], v[98:101], v[130:133], v[78:81]
	v_mfma_f32_16x16x32_bf16 v[82:85], v[102:105], v[130:133], v[86:89]
	s_waitcnt lgkmcnt(10)
	v_mfma_f32_16x16x32_bf16 v[86:89], v[98:101], v[142:145], v[94:97]
	v_mfma_f32_16x16x32_bf16 v[94:97], v[102:105], v[142:145], v[114:117]
	s_waitcnt lgkmcnt(6)
	v_mfma_f32_16x16x32_bf16 v[114:117], v[98:101], v[148:151], v[138:141]
	v_mfma_f32_16x16x32_bf16 v[90:93], v[102:105], v[148:151], v[90:93]
	s_waitcnt lgkmcnt(2)
	v_mfma_f32_16x16x32_bf16 v[66:69], v[98:101], v[70:73], v[66:69]
	v_mfma_f32_16x16x32_bf16 v[70:73], v[102:105], v[70:73], v[74:77]
	v_mfma_f32_16x16x32_bf16 v[74:77], v[106:109], v[134:137], v[78:81]
	v_mfma_f32_16x16x32_bf16 v[78:81], v[110:113], v[134:137], v[82:85]
	v_mfma_f32_16x16x32_bf16 v[82:85], v[106:109], v[152:155], v[86:89]
	v_mfma_f32_16x16x32_bf16 v[86:89], v[110:113], v[152:155], v[94:97]
	v_mfma_f32_16x16x32_bf16 v[94:97], v[106:109], v[156:159], v[114:117]
	v_mfma_f32_16x16x32_bf16 v[90:93], v[110:113], v[156:159], v[90:93]
	s_waitcnt lgkmcnt(0)
	v_mfma_f32_16x16x32_bf16 v[66:69], v[106:109], v[160:163], v[66:69]
	v_mfma_f32_16x16x32_bf16 v[70:73], v[110:113], v[160:163], v[70:73]
	v_add_u32_e32 v98, s1, v128
	s_nop 5
	v_cvt_pk_bf16_f32 v66, v66, v67
	v_cvt_pk_bf16_f32 v67, v68, v69
	v_cvt_pk_bf16_f32 v68, v70, v71
	v_add_u32_e32 v70, 16, v98
	v_cvt_pk_bf16_f32 v74, v74, v75
	v_cvt_pk_bf16_f32 v75, v76, v77
	v_cvt_pk_bf16_f32 v77, v80, v81
	v_cvt_pk_bf16_f32 v80, v86, v87
	v_cvt_pk_bf16_f32 v69, v72, v73
	v_ashrrev_i32_e32 v99, 31, v98
	v_add_u32_e32 v72, 32, v98
	v_add_u32_e32 v86, 48, v98
	v_ashrrev_i32_e32 v71, 31, v70
	v_cvt_pk_bf16_f32 v81, v88, v89
	v_lshlrev_b64 v[88:89], 12, v[98:99]
	v_ashrrev_i32_e32 v73, 31, v72
	v_ashrrev_i32_e32 v87, 31, v86
	v_lshlrev_b64 v[70:71], 12, v[70:71]
	v_cvt_pk_bf16_f32 v76, v78, v79
	v_cvt_pk_bf16_f32 v78, v82, v83
	v_cvt_pk_bf16_f32 v79, v84, v85
	v_lshl_add_u64 v[88:89], v[120:121], 0, v[88:89]
	v_lshlrev_b64 v[72:73], 12, v[72:73]
	v_lshlrev_b64 v[86:87], 12, v[86:87]
	v_lshl_add_u64 v[70:71], v[120:121], 0, v[70:71]
	v_cvt_pk_bf16_f32 v82, v94, v95
	v_cvt_pk_bf16_f32 v83, v96, v97
	v_cvt_pk_bf16_f32 v84, v90, v91
	v_cvt_pk_bf16_f32 v85, v92, v93
	global_store_dwordx2 v[88:89], v[74:75], off
	global_store_dwordx2 v[88:89], v[76:77], off offset:32
	v_lshl_add_u64 v[72:73], v[120:121], 0, v[72:73]
	v_lshl_add_u64 v[74:75], v[120:121], 0, v[86:87]
	global_store_dwordx2 v[70:71], v[78:79], off
	global_store_dwordx2 v[70:71], v[80:81], off offset:32
	global_store_dwordx2 v[72:73], v[82:83], off
	global_store_dwordx2 v[72:73], v[84:85], off offset:32
	global_store_dwordx2 v[74:75], v[66:67], off
	global_store_dwordx2 v[74:75], v[68:69], off offset:32
	s_waitcnt lgkmcnt(0)
	s_barrier
	s_add_i32 s5, s5, 1
	s_add_i32 s1, s1, 64
	s_cmpk_eq_i32 s1, 0x800
	s_cbranch_scc0 .LBB0_1544
	s_ashr_i32 s1, s0, 31
	s_lshl_b64 s[4:5], s[0:1], 16
	s_add_u32 s4, s8, s4
	s_addc_u32 s5, s9, s5
	v_lshl_add_u64 v[66:67], v[118:119], 2, s[4:5]
	v_lshlrev_b32_e32 v146, 2, v122
	v_lshl_add_u64 v[66:67], v[66:67], 0, v[146:147]
	v_lshlrev_b32_e32 v146, 11, v1
	v_lshl_add_u64 v[68:69], v[66:67], 0, v[146:147]
	global_store_dword v[68:69], v62, off
	global_store_dword v[68:69], v63, off offset:512
	global_store_dword v[68:69], v64, off offset:1024
	global_store_dword v[68:69], v65, off offset:1536
	global_store_dword v[68:69], v58, off offset:64
	global_store_dword v[68:69], v59, off offset:576
	global_store_dword v[68:69], v60, off offset:1088
	global_store_dword v[68:69], v61, off offset:1600
	v_or_b32_e32 v58, 0x2000, v146
	v_mov_b32_e32 v59, v147
	v_lshl_add_u64 v[60:61], v[66:67], 0, v[58:59]
	global_store_dword v[60:61], v54, off
	v_or_b32_e32 v60, 0x2200, v146
	v_mov_b32_e32 v61, v147
	v_lshl_add_u64 v[64:65], v[66:67], 0, v[60:61]
	global_store_dword v[64:65], v55, off
	v_or_b32_e32 v54, 0x2400, v146
	v_mov_b32_e32 v55, v147
	v_lshl_add_u64 v[64:65], v[66:67], 0, v[54:55]
	global_store_dword v[64:65], v56, off
	v_or_b32_e32 v64, 0x2600, v146
	v_mov_b32_e32 v65, v147
	v_lshl_add_u64 v[62:63], v[66:67], 0, 64
	v_lshl_add_u64 v[68:69], v[66:67], 0, v[64:65]
	global_store_dword v[68:69], v57, off
	v_lshl_add_u64 v[56:57], v[62:63], 0, v[58:59]
	global_store_dword v[56:57], v46, off
	v_lshl_add_u64 v[56:57], v[62:63], 0, v[60:61]
	global_store_dword v[56:57], v47, off
	v_lshl_add_u64 v[46:47], v[62:63], 0, v[54:55]
	global_store_dword v[46:47], v48, off
	v_lshl_add_u64 v[46:47], v[62:63], 0, v[64:65]
	global_store_dword v[46:47], v49, off
	v_or_b32_e32 v46, 0x4000, v146
	v_mov_b32_e32 v47, v147
	v_lshl_add_u64 v[48:49], v[66:67], 0, v[46:47]
	global_store_dword v[48:49], v50, off
	v_or_b32_e32 v48, 0x4200, v146
	v_mov_b32_e32 v49, v147
	v_lshl_add_u64 v[54:55], v[66:67], 0, v[48:49]
	global_store_dword v[54:55], v51, off
	v_or_b32_e32 v50, 0x4400, v146
	v_mov_b32_e32 v51, v147
	v_lshl_add_u64 v[46:47], v[62:63], 0, v[46:47]
	v_lshl_add_u64 v[54:55], v[66:67], 0, v[50:51]
	global_store_dword v[46:47], v38, off
	v_lshl_add_u64 v[46:47], v[62:63], 0, v[48:49]
	global_store_dword v[54:55], v52, off
	v_or_b32_e32 v54, 0x4600, v146
	v_mov_b32_e32 v55, v147
	global_store_dword v[46:47], v39, off
	v_lshl_add_u64 v[38:39], v[62:63], 0, v[50:51]
	global_store_dword v[38:39], v40, off
	v_lshl_add_u64 v[38:39], v[62:63], 0, v[54:55]
	global_store_dword v[38:39], v41, off
	v_or_b32_e32 v38, 0x6000, v146
	v_mov_b32_e32 v39, v147
	v_lshl_add_u64 v[40:41], v[66:67], 0, v[38:39]
	global_store_dword v[40:41], v42, off
	v_or_b32_e32 v40, 0x6200, v146
	v_mov_b32_e32 v41, v147
	v_lshl_add_u64 v[46:47], v[66:67], 0, v[40:41]
	global_store_dword v[46:47], v43, off
	v_or_b32_e32 v42, 0x6400, v146
	v_mov_b32_e32 v43, v147
	v_lshl_add_u64 v[38:39], v[62:63], 0, v[38:39]
	v_lshl_add_u64 v[46:47], v[66:67], 0, v[42:43]
	global_store_dword v[38:39], v34, off
	v_lshl_add_u64 v[38:39], v[62:63], 0, v[40:41]
	global_store_dword v[46:47], v44, off
	v_or_b32_e32 v46, 0x6600, v146
	v_mov_b32_e32 v47, v147
	global_store_dword v[38:39], v35, off
	v_lshl_add_u64 v[34:35], v[62:63], 0, v[42:43]
	global_store_dword v[34:35], v36, off
	v_lshl_add_u64 v[34:35], v[62:63], 0, v[46:47]
	global_store_dword v[34:35], v37, off
	v_or_b32_e32 v34, 0x8000, v146
	v_mov_b32_e32 v35, v147
	v_lshl_add_u64 v[36:37], v[66:67], 0, v[34:35]
	global_store_dword v[36:37], v30, off
	v_or_b32_e32 v36, 0x8200, v146
	v_mov_b32_e32 v37, v147
	v_lshl_add_u64 v[38:39], v[66:67], 0, v[36:37]
	global_store_dword v[38:39], v31, off
	v_or_b32_e32 v30, 0x8400, v146
	v_mov_b32_e32 v31, v147
	v_lshl_add_u64 v[38:39], v[66:67], 0, v[30:31]
	global_store_dword v[38:39], v32, off
	v_or_b32_e32 v38, 0x8600, v146
	v_mov_b32_e32 v39, v147
	v_lshl_add_u64 v[40:41], v[66:67], 0, v[38:39]
	global_store_dword v[40:41], v33, off
	v_lshl_add_u64 v[32:33], v[62:63], 0, v[34:35]
	global_store_dword v[32:33], v22, off
	v_lshl_add_u64 v[32:33], v[62:63], 0, v[36:37]
	global_store_dword v[32:33], v23, off
	v_lshl_add_u64 v[22:23], v[62:63], 0, v[30:31]
	global_store_dword v[22:23], v24, off
	v_lshl_add_u64 v[22:23], v[62:63], 0, v[38:39]
	global_store_dword v[22:23], v25, off
	v_or_b32_e32 v22, 0xa000, v146
	v_mov_b32_e32 v23, v147
	v_lshl_add_u64 v[24:25], v[66:67], 0, v[22:23]
	global_store_dword v[24:25], v26, off
	v_or_b32_e32 v24, 0xa200, v146
	v_mov_b32_e32 v25, v147
	v_lshl_add_u64 v[30:31], v[66:67], 0, v[24:25]
	global_store_dword v[30:31], v27, off
	v_or_b32_e32 v26, 0xa400, v146
	v_mov_b32_e32 v27, v147
	v_lshl_add_u64 v[22:23], v[62:63], 0, v[22:23]
	v_lshl_add_u64 v[30:31], v[66:67], 0, v[26:27]
	global_store_dword v[22:23], v14, off
	v_lshl_add_u64 v[22:23], v[62:63], 0, v[24:25]
	global_store_dword v[30:31], v28, off
	v_or_b32_e32 v30, 0xa600, v146
	v_mov_b32_e32 v31, v147
	global_store_dword v[22:23], v15, off
	v_lshl_add_u64 v[14:15], v[62:63], 0, v[26:27]
	global_store_dword v[14:15], v16, off
	v_lshl_add_u64 v[14:15], v[62:63], 0, v[30:31]
	global_store_dword v[14:15], v17, off
	v_or_b32_e32 v14, 0xc000, v146
	v_mov_b32_e32 v15, v147
	v_lshl_add_u64 v[16:17], v[66:67], 0, v[14:15]
	global_store_dword v[16:17], v18, off
	v_or_b32_e32 v16, 0xc200, v146
	v_mov_b32_e32 v17, v147
	v_lshl_add_u64 v[22:23], v[66:67], 0, v[16:17]
	global_store_dword v[22:23], v19, off
	v_or_b32_e32 v18, 0xc400, v146
	v_mov_b32_e32 v19, v147
	v_lshl_add_u64 v[14:15], v[62:63], 0, v[14:15]
	v_lshl_add_u64 v[22:23], v[66:67], 0, v[18:19]
	global_store_dword v[14:15], v6, off
	v_lshl_add_u64 v[14:15], v[62:63], 0, v[16:17]
	global_store_dword v[22:23], v20, off
	v_or_b32_e32 v22, 0xc600, v146
	v_mov_b32_e32 v23, v147
	global_store_dword v[14:15], v7, off
	v_lshl_add_u64 v[6:7], v[62:63], 0, v[18:19]
	global_store_dword v[6:7], v8, off
	v_lshl_add_u64 v[6:7], v[62:63], 0, v[22:23]
	global_store_dword v[6:7], v9, off
	v_or_b32_e32 v6, 0xe000, v146
	v_mov_b32_e32 v7, v147
	v_lshl_add_u64 v[8:9], v[66:67], 0, v[6:7]
	global_store_dword v[8:9], v10, off
	v_or_b32_e32 v8, 0xe200, v146
	v_mov_b32_e32 v9, v147
	v_lshl_add_u64 v[14:15], v[66:67], 0, v[8:9]
	v_lshl_add_u64 v[6:7], v[62:63], 0, v[6:7]
	global_store_dword v[14:15], v11, off
	v_or_b32_e32 v10, 0xe400, v146
	v_mov_b32_e32 v11, v147
	global_store_dword v[6:7], v2, off
	v_lshl_add_u64 v[6:7], v[62:63], 0, v[8:9]
	v_lshl_add_u64 v[14:15], v[66:67], 0, v[10:11]
	v_or_b32_e32 v146, 0xe600, v146
	global_store_dword v[6:7], v3, off
	v_lshl_add_u64 v[2:3], v[62:63], 0, v[10:11]
	v_lshl_add_u64 v[56:57], v[66:67], 0, v[54:55]
	v_lshl_add_u64 v[48:49], v[66:67], 0, v[46:47]
	v_lshl_add_u64 v[32:33], v[66:67], 0, v[30:31]
	v_lshl_add_u64 v[24:25], v[66:67], 0, v[22:23]
	global_store_dword v[14:15], v12, off
	v_lshl_add_u64 v[14:15], v[66:67], 0, v[146:147]
	global_store_dword v[2:3], v4, off
	v_lshl_add_u64 v[2:3], v[62:63], 0, v[146:147]
	global_store_dword v[56:57], v53, off
	global_store_dword v[48:49], v45, off
	global_store_dword v[32:33], v29, off
	global_store_dword v[24:25], v21, off
	global_store_dword v[14:15], v13, off
	global_store_dword v[2:3], v5, off
